# resid GEMM epilogues: x_old loads batched 16 deep with counted vmcnt (was load-wait-store ladder); plus attn stagger
# speedup vs baseline: 1.0037x; 1.0037x over previous
;     __device__ __forceinline__ void operator()(const f32x4 (&acc)[2][2][4][2], const Unit& u, int wr, int wc, int fr, int fq) const {
;         const int cond = u.pm < 64 ? 0 : (u.pm < 128 ? 1 : 2);
;         const float* gate = gate_l + cond * 9216;
;         const int col0 = u.pn * BM + wc * 32 + 4 * fq;
;         f32x4 gv[2][2];
; #pragma unroll
;         for (int bj = 0; bj < 2; ++bj)
; #pragma unroll
;             for (int n = 0; n < 2; ++n) gv[bj][n] = *(const f32x4*)(gate + col0 + bj * HALF + n * 16) * coef;
; #pragma unroll
;         for (int ai = 0; ai < 2; ++ai)
; #pragma unroll
;             for (int m = 0; m < 4; ++m) {
;                 const int row = u.pm * BM + ai * HALF + wr * 64 + m * 16 + fr;
;                 const float* s = row < MX_ ? src_main + (size_t)row * D_ : src_ctx + (size_t)(row - MX_) * D_;
;                 float* d = row < MX_ ? dst_main + (size_t)row * D_ : dst_ctx + (size_t)(row - MX_) * D_;
; #pragma unroll
;                 for (int bj = 0; bj < 2; ++bj)
; #pragma unroll
;                     for (int n = 0; n < 2; ++n) { const int off = col0 + bj * HALF + n * 16; const f32x4 xo = *(const f32x4*)(s + off); *(f32x4*)(d + off) = xo + gv[bj][n] * acc[ai][bj][m][n]; }
.LBB0_315:
	s_cmpk_lt_i32 s65, 0x80
	s_cselect_b32 s16, s62, 0x4800
	s_cmp_gt_i32 s65, 63
	s_cselect_b32 s16, s16, 0
	s_lshl_b32 s16, s16, 2
	s_add_u32 s26, s53, s16
	s_addc_u32 s27, s54, 0
	v_lshl_add_u32 v144, s65, 8, v146
	v_lshl_or_b32 v145, s66, 8, v148
	v_lshlrev_b32_e32 v184, 2, v145
	v_lshl_add_u32 v207, v144, 12, v184
	global_load_dwordx4 v[222:225], v184, s[26:27]
	global_load_dwordx4 v[226:229], v184, s[26:27] offset:64
	global_load_dwordx4 v[230:233], v184, s[26:27] offset:512
	global_load_dwordx4 v[234:237], v184, s[26:27] offset:576
	v_add_u32_e32 v213, 0x10000, v207
	v_add_u32_e32 v218, 0x20000, v207
	v_add_u32_e32 v219, 0x30000, v207
	v_add_u32_e32 v250, 0x80000, v207
	v_add_u32_e32 v251, 0x90000, v207
	v_add_u32_e32 v238, 0xa0000, v207
	v_add_u32_e32 v239, 0xb0000, v207
	global_load_dwordx4 v[140:143], v207, s[8:9]
	global_load_dwordx4 v[152:155], v207, s[8:9] offset:64
	global_load_dwordx4 v[156:159], v207, s[8:9] offset:512
	global_load_dwordx4 v[160:163], v207, s[8:9] offset:576
	global_load_dwordx4 v[164:167], v213, s[8:9]
	global_load_dwordx4 v[168:171], v213, s[8:9] offset:64
	global_load_dwordx4 v[172:175], v213, s[8:9] offset:512
	global_load_dwordx4 v[176:179], v213, s[8:9] offset:576
	global_load_dwordx4 v[180:183], v218, s[8:9]
	global_load_dwordx4 v[186:189], v218, s[8:9] offset:64
	global_load_dwordx4 v[190:193], v218, s[8:9] offset:512
	global_load_dwordx4 v[194:197], v218, s[8:9] offset:576
	global_load_dwordx4 v[198:201], v219, s[8:9]
	global_load_dwordx4 v[202:205], v219, s[8:9] offset:64
	global_load_dwordx4 v[208:211], v219, s[8:9] offset:512
	global_load_dwordx4 v[214:217], v219, s[8:9] offset:576
	s_waitcnt vmcnt(16)
	v_pk_mul_f32 v[222:223], v[222:223], 0.5 op_sel_hi:[1,0]
	v_pk_mul_f32 v[224:225], v[224:225], 0.5 op_sel_hi:[1,0]
	v_pk_mul_f32 v[226:227], v[226:227], 0.5 op_sel_hi:[1,0]
	v_pk_mul_f32 v[228:229], v[228:229], 0.5 op_sel_hi:[1,0]
	v_pk_mul_f32 v[230:231], v[230:231], 0.5 op_sel_hi:[1,0]
	v_pk_mul_f32 v[232:233], v[232:233], 0.5 op_sel_hi:[1,0]
	v_pk_mul_f32 v[234:235], v[234:235], 0.5 op_sel_hi:[1,0]
	v_pk_mul_f32 v[236:237], v[236:237], 0.5 op_sel_hi:[1,0]
	s_waitcnt vmcnt(15)
	v_pk_fma_f32 v[124:125], v[124:125], v[222:223], v[140:141]
	v_pk_fma_f32 v[126:127], v[126:127], v[224:225], v[142:143]
	s_waitcnt vmcnt(14)
	v_pk_fma_f32 v[120:121], v[120:121], v[226:227], v[152:153]
	v_pk_fma_f32 v[122:123], v[122:123], v[228:229], v[154:155]
	s_waitcnt vmcnt(13)
	v_pk_fma_f32 v[116:117], v[116:117], v[230:231], v[156:157]
	v_pk_fma_f32 v[118:119], v[118:119], v[232:233], v[158:159]
	s_waitcnt vmcnt(12)
	v_pk_fma_f32 v[108:109], v[108:109], v[234:235], v[160:161]
	v_pk_fma_f32 v[110:111], v[110:111], v[236:237], v[162:163]
	global_store_dwordx4 v207, v[124:127], s[10:11]
	global_store_dwordx4 v207, v[120:123], s[10:11] offset:64
	global_store_dwordx4 v207, v[116:119], s[10:11] offset:512
	global_store_dwordx4 v207, v[108:111], s[10:11] offset:576
	global_load_dwordx4 v[140:143], v250, s[8:9]
	global_load_dwordx4 v[152:155], v250, s[8:9] offset:64
	global_load_dwordx4 v[156:159], v250, s[8:9] offset:512
	global_load_dwordx4 v[160:163], v250, s[8:9] offset:576
	s_waitcnt vmcnt(19)
	v_pk_fma_f32 v[112:113], v[112:113], v[222:223], v[164:165]
	v_pk_fma_f32 v[114:115], v[114:115], v[224:225], v[166:167]
	s_waitcnt vmcnt(18)
	v_pk_fma_f32 v[104:105], v[104:105], v[226:227], v[168:169]
	v_pk_fma_f32 v[106:107], v[106:107], v[228:229], v[170:171]
	s_waitcnt vmcnt(17)
	v_pk_fma_f32 v[100:101], v[100:101], v[230:231], v[172:173]
	v_pk_fma_f32 v[102:103], v[102:103], v[232:233], v[174:175]
	s_waitcnt vmcnt(16)
	v_pk_fma_f32 v[92:93], v[92:93], v[234:235], v[176:177]
	v_pk_fma_f32 v[94:95], v[94:95], v[236:237], v[178:179]
	global_store_dwordx4 v213, v[112:115], s[10:11]
	global_store_dwordx4 v213, v[104:107], s[10:11] offset:64
	global_store_dwordx4 v213, v[100:103], s[10:11] offset:512
	global_store_dwordx4 v213, v[92:95], s[10:11] offset:576
	global_load_dwordx4 v[164:167], v251, s[8:9]
	global_load_dwordx4 v[168:171], v251, s[8:9] offset:64
	global_load_dwordx4 v[172:175], v251, s[8:9] offset:512
	global_load_dwordx4 v[176:179], v251, s[8:9] offset:576
	s_waitcnt vmcnt(23)
	v_pk_fma_f32 v[96:97], v[96:97], v[222:223], v[180:181]
	v_pk_fma_f32 v[98:99], v[98:99], v[224:225], v[182:183]
	s_waitcnt vmcnt(22)
	v_pk_fma_f32 v[88:89], v[88:89], v[226:227], v[186:187]
	v_pk_fma_f32 v[90:91], v[90:91], v[228:229], v[188:189]
	s_waitcnt vmcnt(21)
	v_pk_fma_f32 v[84:85], v[84:85], v[230:231], v[190:191]
	v_pk_fma_f32 v[86:87], v[86:87], v[232:233], v[192:193]
	s_waitcnt vmcnt(20)
; #define PG8_BAR __builtin_amdgcn_s_barrier()
;     __device__ __forceinline__ void operator()(const f32x4 (&acc)[2][2][4][2], const Unit& u, int wr, int wc, int fr, int fq) const {
;     ...
;             for (int m = 0; m < 4; ++m) {
;                 const int row = u.pm * BM + ai * HALF + wr * 64 + m * 16 + fr;
;                 const float* s = row < MX_ ? src_main + (size_t)row * D_ : src_ctx + (size_t)(row - MX_) * D_;
;                 float* d = row < MX_ ? dst_main + (size_t)row * D_ : dst_ctx + (size_t)(row - MX_) * D_;
; #pragma unroll
;                 for (int bj = 0; bj < 2; ++bj)
; #pragma unroll
;                     for (int n = 0; n < 2; ++n) { const int off = col0 + bj * HALF + n * 16; const f32x4 xo = *(const f32x4*)(s + off); *(f32x4*)(d + off) = xo + gv[bj][n] * acc[ai][bj][m][n]; }
;     ...
;         if (!has_next) break;
; #pragma unroll
;         for (int a = 0; a < 2; ++a)
; #pragma unroll
;             for (int b = 0; b < 2; ++b)
; #pragma unroll
;                 for (int m = 0; m < 4; ++m)
; #pragma unroll
;                     for (int n = 0; n < 2; ++n) acc[a][b][m][n] = (f32x4){0.f, 0.f, 0.f, 0.f};
;         cur = nxt; cA = nA; cB = nB; ++ui;
;         if constexpr (ALIGN_EPI) { if (wr == 1) PG8_BAR; }
	v_pk_fma_f32 v[76:77], v[76:77], v[234:235], v[194:195]
	v_pk_fma_f32 v[78:79], v[78:79], v[236:237], v[196:197]
	global_store_dwordx4 v218, v[96:99], s[10:11]
	global_store_dwordx4 v218, v[88:91], s[10:11] offset:64
	global_store_dwordx4 v218, v[84:87], s[10:11] offset:512
	global_store_dwordx4 v218, v[76:79], s[10:11] offset:576
	global_load_dwordx4 v[180:183], v238, s[8:9]
	global_load_dwordx4 v[186:189], v238, s[8:9] offset:64
	global_load_dwordx4 v[190:193], v238, s[8:9] offset:512
	global_load_dwordx4 v[194:197], v238, s[8:9] offset:576
	s_waitcnt vmcnt(27)
	v_pk_fma_f32 v[80:81], v[80:81], v[222:223], v[198:199]
	v_pk_fma_f32 v[82:83], v[82:83], v[224:225], v[200:201]
	s_waitcnt vmcnt(26)
	v_pk_fma_f32 v[72:73], v[72:73], v[226:227], v[202:203]
	v_pk_fma_f32 v[74:75], v[74:75], v[228:229], v[204:205]
	s_waitcnt vmcnt(25)
	v_pk_fma_f32 v[68:69], v[68:69], v[230:231], v[208:209]
	v_pk_fma_f32 v[70:71], v[70:71], v[232:233], v[210:211]
	s_waitcnt vmcnt(24)
	v_pk_fma_f32 v[64:65], v[64:65], v[234:235], v[214:215]
	v_pk_fma_f32 v[66:67], v[66:67], v[236:237], v[216:217]
	global_store_dwordx4 v219, v[80:83], s[10:11]
	global_store_dwordx4 v219, v[72:75], s[10:11] offset:64
	global_store_dwordx4 v219, v[68:71], s[10:11] offset:512
	global_store_dwordx4 v219, v[64:67], s[10:11] offset:576
	global_load_dwordx4 v[198:201], v239, s[8:9]
	global_load_dwordx4 v[202:205], v239, s[8:9] offset:64
	global_load_dwordx4 v[208:211], v239, s[8:9] offset:512
	global_load_dwordx4 v[214:217], v239, s[8:9] offset:576
	s_waitcnt vmcnt(27)
	v_pk_fma_f32 v[60:61], v[60:61], v[222:223], v[140:141]
	v_pk_fma_f32 v[62:63], v[62:63], v[224:225], v[142:143]
	s_waitcnt vmcnt(26)
	v_pk_fma_f32 v[56:57], v[56:57], v[226:227], v[152:153]
	v_pk_fma_f32 v[58:59], v[58:59], v[228:229], v[154:155]
	s_waitcnt vmcnt(25)
	v_pk_fma_f32 v[52:53], v[52:53], v[230:231], v[156:157]
	v_pk_fma_f32 v[54:55], v[54:55], v[232:233], v[158:159]
	s_waitcnt vmcnt(24)
	v_pk_fma_f32 v[44:45], v[44:45], v[234:235], v[160:161]
	v_pk_fma_f32 v[46:47], v[46:47], v[236:237], v[162:163]
	global_store_dwordx4 v250, v[60:63], s[10:11]
	global_store_dwordx4 v250, v[56:59], s[10:11] offset:64
	global_store_dwordx4 v250, v[52:55], s[10:11] offset:512
	global_store_dwordx4 v250, v[44:47], s[10:11] offset:576
	s_waitcnt vmcnt(23)
	v_pk_fma_f32 v[48:49], v[48:49], v[222:223], v[164:165]
	v_pk_fma_f32 v[50:51], v[50:51], v[224:225], v[166:167]
	s_waitcnt vmcnt(22)
	v_pk_fma_f32 v[40:41], v[40:41], v[226:227], v[168:169]
	v_pk_fma_f32 v[42:43], v[42:43], v[228:229], v[170:171]
	s_waitcnt vmcnt(21)
	v_pk_fma_f32 v[36:37], v[36:37], v[230:231], v[172:173]
	v_pk_fma_f32 v[38:39], v[38:39], v[232:233], v[174:175]
	s_waitcnt vmcnt(20)
	v_pk_fma_f32 v[28:29], v[28:29], v[234:235], v[176:177]
	v_pk_fma_f32 v[30:31], v[30:31], v[236:237], v[178:179]
	global_store_dwordx4 v251, v[48:51], s[10:11]
	global_store_dwordx4 v251, v[40:43], s[10:11] offset:64
	global_store_dwordx4 v251, v[36:39], s[10:11] offset:512
	global_store_dwordx4 v251, v[28:31], s[10:11] offset:576
	s_waitcnt vmcnt(19)
	v_pk_fma_f32 v[32:33], v[32:33], v[222:223], v[180:181]
	v_pk_fma_f32 v[34:35], v[34:35], v[224:225], v[182:183]
	s_waitcnt vmcnt(18)
	v_pk_fma_f32 v[24:25], v[24:25], v[226:227], v[186:187]
	v_pk_fma_f32 v[26:27], v[26:27], v[228:229], v[188:189]
	s_waitcnt vmcnt(17)
	v_pk_fma_f32 v[20:21], v[20:21], v[230:231], v[190:191]
	v_pk_fma_f32 v[22:23], v[22:23], v[232:233], v[192:193]
	s_waitcnt vmcnt(16)
	v_pk_fma_f32 v[12:13], v[12:13], v[234:235], v[194:195]
	v_pk_fma_f32 v[14:15], v[14:15], v[236:237], v[196:197]
	global_store_dwordx4 v238, v[32:35], s[10:11]
	global_store_dwordx4 v238, v[24:27], s[10:11] offset:64
	global_store_dwordx4 v238, v[20:23], s[10:11] offset:512
	global_store_dwordx4 v238, v[12:15], s[10:11] offset:576
	s_waitcnt vmcnt(15)
	v_pk_fma_f32 v[16:17], v[16:17], v[222:223], v[198:199]
	v_pk_fma_f32 v[18:19], v[18:19], v[224:225], v[200:201]
	s_waitcnt vmcnt(14)
	v_pk_fma_f32 v[8:9], v[8:9], v[226:227], v[202:203]
	v_pk_fma_f32 v[10:11], v[10:11], v[228:229], v[204:205]
	s_waitcnt vmcnt(13)
	v_pk_fma_f32 v[4:5], v[4:5], v[230:231], v[208:209]
	v_pk_fma_f32 v[6:7], v[6:7], v[232:233], v[210:211]
	s_waitcnt vmcnt(12)
	v_pk_fma_f32 v[0:1], v[0:1], v[234:235], v[214:215]
	v_pk_fma_f32 v[2:3], v[2:3], v[236:237], v[216:217]
	global_store_dwordx4 v239, v[16:19], s[10:11]
	global_store_dwordx4 v239, v[8:11], s[10:11] offset:64
	global_store_dwordx4 v239, v[4:7], s[10:11] offset:512
	global_store_dwordx4 v239, v[0:3], s[10:11] offset:576
	s_and_b64 vcc, exec, s[4:5]
	s_mov_b64 s[4:5], -1
	s_cbranch_vccnz .LBB0_300
	s_andn2_b64 vcc, exec, s[12:13]
	s_cbranch_vccnz .LBB0_299
	s_barrier
	s_branch .LBB0_299

;     __device__ __forceinline__ void operator()(const f32x4 (&acc)[2][2][4][2], const Unit& u, int wr, int wc, int fr, int fq) const {
;         const int cond = u.pm < 64 ? 0 : (u.pm < 128 ? 1 : 2);
;         const float* gate = gate_l + cond * 9216;
;         const int col0 = u.pn * BM + wc * 32 + 4 * fq;
;         f32x4 gv[2][2];
; #pragma unroll
;         for (int bj = 0; bj < 2; ++bj)
; #pragma unroll
;             for (int n = 0; n < 2; ++n) gv[bj][n] = *(const f32x4*)(gate + col0 + bj * HALF + n * 16) * coef;
; #pragma unroll
;         for (int ai = 0; ai < 2; ++ai)
; #pragma unroll
;             for (int m = 0; m < 4; ++m) {
;                 const int row = u.pm * BM + ai * HALF + wr * 64 + m * 16 + fr;
;                 const float* s = row < MX_ ? src_main + (size_t)row * D_ : src_ctx + (size_t)(row - MX_) * D_;
;                 float* d = row < MX_ ? dst_main + (size_t)row * D_ : dst_ctx + (size_t)(row - MX_) * D_;
; #pragma unroll
;                 for (int bj = 0; bj < 2; ++bj)
; #pragma unroll
;                     for (int n = 0; n < 2; ++n) { const int off = col0 + bj * HALF + n * 16; const f32x4 xo = *(const f32x4*)(s + off); *(f32x4*)(d + off) = xo + gv[bj][n] * acc[ai][bj][m][n]; }
.LBB0_1126:
	s_cmpk_lt_i32 s40, 0x80
	s_cselect_b32 s7, s69, 0x4800
	s_cmp_gt_i32 s40, 63
	s_cselect_b32 s7, s7, 0
	s_lshl_b32 s7, s7, 2
	s_add_u32 s8, s61, s7
	s_addc_u32 s9, s62, 0
	v_lshl_add_u32 v156, s40, 8, v158
	v_lshl_or_b32 v157, s6, 8, v160
	v_lshlrev_b32_e32 v201, 2, v157
	v_lshl_add_u32 v240, v156, 12, v201
	global_load_dwordx4 v[224:227], v201, s[8:9]
	global_load_dwordx4 v[228:231], v201, s[8:9] offset:64
	global_load_dwordx4 v[232:235], v201, s[8:9] offset:512
	global_load_dwordx4 v[236:239], v201, s[8:9] offset:576
	v_add_u32_e32 v241, 0x10000, v240
	v_add_u32_e32 v242, 0x20000, v240
	v_add_u32_e32 v243, 0x30000, v240
	v_add_u32_e32 v244, 0x80000, v240
	v_add_u32_e32 v245, 0x90000, v240
	v_add_u32_e32 v246, 0xa0000, v240
	v_add_u32_e32 v247, 0xb0000, v240
	global_load_dwordx4 v[128:131], v240, s[12:13]
	global_load_dwordx4 v[132:135], v240, s[12:13] offset:64
	global_load_dwordx4 v[136:139], v240, s[12:13] offset:512
	global_load_dwordx4 v[140:143], v240, s[12:13] offset:576
	global_load_dwordx4 v[164:167], v241, s[12:13]
	global_load_dwordx4 v[168:171], v241, s[12:13] offset:64
	global_load_dwordx4 v[172:175], v241, s[12:13] offset:512
	global_load_dwordx4 v[176:179], v241, s[12:13] offset:576
	global_load_dwordx4 v[180:183], v242, s[12:13]
	global_load_dwordx4 v[184:187], v242, s[12:13] offset:64
	global_load_dwordx4 v[188:191], v242, s[12:13] offset:512
	global_load_dwordx4 v[192:195], v242, s[12:13] offset:576
	global_load_dwordx4 v[196:199], v243, s[12:13]
	global_load_dwordx4 v[212:215], v243, s[12:13] offset:64
	global_load_dwordx4 v[216:219], v243, s[12:13] offset:512
	global_load_dwordx4 v[220:223], v243, s[12:13] offset:576
	s_waitcnt vmcnt(16)
	s_waitcnt vmcnt(15)
	v_pk_fma_f32 v[124:125], v[124:125], v[224:225], v[128:129]
	v_pk_fma_f32 v[126:127], v[126:127], v[226:227], v[130:131]
	s_waitcnt vmcnt(14)
	v_pk_fma_f32 v[120:121], v[120:121], v[228:229], v[132:133]
	v_pk_fma_f32 v[122:123], v[122:123], v[230:231], v[134:135]
	s_waitcnt vmcnt(13)
	v_pk_fma_f32 v[116:117], v[116:117], v[232:233], v[136:137]
	v_pk_fma_f32 v[118:119], v[118:119], v[234:235], v[138:139]
	s_waitcnt vmcnt(12)
	v_pk_fma_f32 v[112:113], v[112:113], v[236:237], v[140:141]
	v_pk_fma_f32 v[114:115], v[114:115], v[238:239], v[142:143]
	global_store_dwordx4 v240, v[124:127], s[12:13]
	global_store_dwordx4 v240, v[120:123], s[12:13] offset:64
	global_store_dwordx4 v240, v[116:119], s[12:13] offset:512
	global_store_dwordx4 v240, v[112:115], s[12:13] offset:576
	global_load_dwordx4 v[128:131], v244, s[12:13]
	global_load_dwordx4 v[132:135], v244, s[12:13] offset:64
	global_load_dwordx4 v[136:139], v244, s[12:13] offset:512
	global_load_dwordx4 v[140:143], v244, s[12:13] offset:576
	s_waitcnt vmcnt(19)
	v_pk_fma_f32 v[108:109], v[108:109], v[224:225], v[164:165]
	v_pk_fma_f32 v[110:111], v[110:111], v[226:227], v[166:167]
	s_waitcnt vmcnt(18)
	v_pk_fma_f32 v[104:105], v[104:105], v[228:229], v[168:169]
	v_pk_fma_f32 v[106:107], v[106:107], v[230:231], v[170:171]
	s_waitcnt vmcnt(17)
	v_pk_fma_f32 v[100:101], v[100:101], v[232:233], v[172:173]
	v_pk_fma_f32 v[102:103], v[102:103], v[234:235], v[174:175]
	s_waitcnt vmcnt(16)
	v_pk_fma_f32 v[96:97], v[96:97], v[236:237], v[176:177]
	v_pk_fma_f32 v[98:99], v[98:99], v[238:239], v[178:179]
	global_store_dwordx4 v241, v[108:111], s[12:13]
	global_store_dwordx4 v241, v[104:107], s[12:13] offset:64
	global_store_dwordx4 v241, v[100:103], s[12:13] offset:512
	global_store_dwordx4 v241, v[96:99], s[12:13] offset:576
	global_load_dwordx4 v[164:167], v245, s[12:13]
	global_load_dwordx4 v[168:171], v245, s[12:13] offset:64
	global_load_dwordx4 v[172:175], v245, s[12:13] offset:512
	global_load_dwordx4 v[176:179], v245, s[12:13] offset:576
	s_waitcnt vmcnt(23)
	v_pk_fma_f32 v[92:93], v[92:93], v[224:225], v[180:181]
	v_pk_fma_f32 v[94:95], v[94:95], v[226:227], v[182:183]
	s_waitcnt vmcnt(22)
	v_pk_fma_f32 v[88:89], v[88:89], v[228:229], v[184:185]
	v_pk_fma_f32 v[90:91], v[90:91], v[230:231], v[186:187]
	s_waitcnt vmcnt(21)
	v_pk_fma_f32 v[84:85], v[84:85], v[232:233], v[188:189]
	v_pk_fma_f32 v[86:87], v[86:87], v[234:235], v[190:191]
	s_waitcnt vmcnt(20)
; #define PG8_BAR __builtin_amdgcn_s_barrier()
;     __device__ __forceinline__ void operator()(const f32x4 (&acc)[2][2][4][2], const Unit& u, int wr, int wc, int fr, int fq) const {
;     ...
;             for (int m = 0; m < 4; ++m) {
;                 const int row = u.pm * BM + ai * HALF + wr * 64 + m * 16 + fr;
;                 const float* s = row < MX_ ? src_main + (size_t)row * D_ : src_ctx + (size_t)(row - MX_) * D_;
;                 float* d = row < MX_ ? dst_main + (size_t)row * D_ : dst_ctx + (size_t)(row - MX_) * D_;
; #pragma unroll
;                 for (int bj = 0; bj < 2; ++bj)
; #pragma unroll
;                     for (int n = 0; n < 2; ++n) { const int off = col0 + bj * HALF + n * 16; const f32x4 xo = *(const f32x4*)(s + off); *(f32x4*)(d + off) = xo + gv[bj][n] * acc[ai][bj][m][n]; }
;     ...
;         if (!has_next) break;
; #pragma unroll
;         for (int a = 0; a < 2; ++a)
; #pragma unroll
;             for (int b = 0; b < 2; ++b)
; #pragma unroll
;                 for (int m = 0; m < 4; ++m)
; #pragma unroll
;                     for (int n = 0; n < 2; ++n) acc[a][b][m][n] = (f32x4){0.f, 0.f, 0.f, 0.f};
;         cur = nxt; cA = nA; cB = nB; ++ui;
;         if constexpr (ALIGN_EPI) { if (wr == 1) PG8_BAR; }
	v_pk_fma_f32 v[80:81], v[80:81], v[236:237], v[192:193]
	v_pk_fma_f32 v[82:83], v[82:83], v[238:239], v[194:195]
	global_store_dwordx4 v242, v[92:95], s[12:13]
	global_store_dwordx4 v242, v[88:91], s[12:13] offset:64
	global_store_dwordx4 v242, v[84:87], s[12:13] offset:512
	global_store_dwordx4 v242, v[80:83], s[12:13] offset:576
	global_load_dwordx4 v[180:183], v246, s[12:13]
	global_load_dwordx4 v[184:187], v246, s[12:13] offset:64
	global_load_dwordx4 v[188:191], v246, s[12:13] offset:512
	global_load_dwordx4 v[192:195], v246, s[12:13] offset:576
	s_waitcnt vmcnt(27)
	v_pk_fma_f32 v[76:77], v[76:77], v[224:225], v[196:197]
	v_pk_fma_f32 v[78:79], v[78:79], v[226:227], v[198:199]
	s_waitcnt vmcnt(26)
	v_pk_fma_f32 v[72:73], v[72:73], v[228:229], v[212:213]
	v_pk_fma_f32 v[74:75], v[74:75], v[230:231], v[214:215]
	s_waitcnt vmcnt(25)
	v_pk_fma_f32 v[68:69], v[68:69], v[232:233], v[216:217]
	v_pk_fma_f32 v[70:71], v[70:71], v[234:235], v[218:219]
	s_waitcnt vmcnt(24)
	v_pk_fma_f32 v[64:65], v[64:65], v[236:237], v[220:221]
	v_pk_fma_f32 v[66:67], v[66:67], v[238:239], v[222:223]
	global_store_dwordx4 v243, v[76:79], s[12:13]
	global_store_dwordx4 v243, v[72:75], s[12:13] offset:64
	global_store_dwordx4 v243, v[68:71], s[12:13] offset:512
	global_store_dwordx4 v243, v[64:67], s[12:13] offset:576
	global_load_dwordx4 v[196:199], v247, s[12:13]
	global_load_dwordx4 v[212:215], v247, s[12:13] offset:64
	global_load_dwordx4 v[216:219], v247, s[12:13] offset:512
	global_load_dwordx4 v[220:223], v247, s[12:13] offset:576
	s_waitcnt vmcnt(27)
	v_pk_fma_f32 v[60:61], v[60:61], v[224:225], v[128:129]
	v_pk_fma_f32 v[62:63], v[62:63], v[226:227], v[130:131]
	s_waitcnt vmcnt(26)
	v_pk_fma_f32 v[56:57], v[56:57], v[228:229], v[132:133]
	v_pk_fma_f32 v[58:59], v[58:59], v[230:231], v[134:135]
	s_waitcnt vmcnt(25)
	v_pk_fma_f32 v[52:53], v[52:53], v[232:233], v[136:137]
	v_pk_fma_f32 v[54:55], v[54:55], v[234:235], v[138:139]
	s_waitcnt vmcnt(24)
	v_pk_fma_f32 v[48:49], v[48:49], v[236:237], v[140:141]
	v_pk_fma_f32 v[50:51], v[50:51], v[238:239], v[142:143]
	global_store_dwordx4 v244, v[60:63], s[12:13]
	global_store_dwordx4 v244, v[56:59], s[12:13] offset:64
	global_store_dwordx4 v244, v[52:55], s[12:13] offset:512
	global_store_dwordx4 v244, v[48:51], s[12:13] offset:576
	s_waitcnt vmcnt(23)
	v_pk_fma_f32 v[44:45], v[44:45], v[224:225], v[164:165]
	v_pk_fma_f32 v[46:47], v[46:47], v[226:227], v[166:167]
	s_waitcnt vmcnt(22)
	v_pk_fma_f32 v[40:41], v[40:41], v[228:229], v[168:169]
	v_pk_fma_f32 v[42:43], v[42:43], v[230:231], v[170:171]
	s_waitcnt vmcnt(21)
	v_pk_fma_f32 v[36:37], v[36:37], v[232:233], v[172:173]
	v_pk_fma_f32 v[38:39], v[38:39], v[234:235], v[174:175]
	s_waitcnt vmcnt(20)
	v_pk_fma_f32 v[32:33], v[32:33], v[236:237], v[176:177]
	v_pk_fma_f32 v[34:35], v[34:35], v[238:239], v[178:179]
	global_store_dwordx4 v245, v[44:47], s[12:13]
	global_store_dwordx4 v245, v[40:43], s[12:13] offset:64
	global_store_dwordx4 v245, v[36:39], s[12:13] offset:512
	global_store_dwordx4 v245, v[32:35], s[12:13] offset:576
	s_waitcnt vmcnt(19)
	v_pk_fma_f32 v[28:29], v[28:29], v[224:225], v[180:181]
	v_pk_fma_f32 v[30:31], v[30:31], v[226:227], v[182:183]
	s_waitcnt vmcnt(18)
	v_pk_fma_f32 v[24:25], v[24:25], v[228:229], v[184:185]
	v_pk_fma_f32 v[26:27], v[26:27], v[230:231], v[186:187]
	s_waitcnt vmcnt(17)
	v_pk_fma_f32 v[20:21], v[20:21], v[232:233], v[188:189]
	v_pk_fma_f32 v[22:23], v[22:23], v[234:235], v[190:191]
	s_waitcnt vmcnt(16)
	v_pk_fma_f32 v[16:17], v[16:17], v[236:237], v[192:193]
	v_pk_fma_f32 v[18:19], v[18:19], v[238:239], v[194:195]
	global_store_dwordx4 v246, v[28:31], s[12:13]
	global_store_dwordx4 v246, v[24:27], s[12:13] offset:64
	global_store_dwordx4 v246, v[20:23], s[12:13] offset:512
	global_store_dwordx4 v246, v[16:19], s[12:13] offset:576
	s_waitcnt vmcnt(15)
	v_pk_fma_f32 v[12:13], v[12:13], v[224:225], v[196:197]
	v_pk_fma_f32 v[14:15], v[14:15], v[226:227], v[198:199]
	s_waitcnt vmcnt(14)
	v_pk_fma_f32 v[8:9], v[8:9], v[228:229], v[212:213]
	v_pk_fma_f32 v[10:11], v[10:11], v[230:231], v[214:215]
	s_waitcnt vmcnt(13)
	v_pk_fma_f32 v[4:5], v[4:5], v[232:233], v[216:217]
	v_pk_fma_f32 v[6:7], v[6:7], v[234:235], v[218:219]
	s_waitcnt vmcnt(12)
	v_pk_fma_f32 v[0:1], v[0:1], v[236:237], v[220:221]
	v_pk_fma_f32 v[2:3], v[2:3], v[238:239], v[222:223]
	global_store_dwordx4 v247, v[12:15], s[12:13]
	global_store_dwordx4 v247, v[8:11], s[12:13] offset:64
	global_store_dwordx4 v247, v[4:7], s[12:13] offset:512
	global_store_dwordx4 v247, v[0:3], s[12:13] offset:576
	s_andn2_b64 vcc, exec, s[10:11]
	s_mov_b64 s[10:11], -1
	s_cbranch_vccnz .LBB0_1115
	s_andn2_b64 vcc, exec, s[14:15]
	s_cbranch_vccnz .LBB0_1114
	s_barrier
	s_branch .LBB0_1114

;     __device__ __forceinline__ void operator()(const f32x4 (&acc)[2][2][4][2], const Unit& u, int wr, int wc, int fr, int fq) const {
;         const int cond = u.pm < 64 ? 0 : (u.pm < 128 ? 1 : 2);
;         const float* gate = gate_l + cond * 9216;
;         const int col0 = u.pn * BM + wc * 32 + 4 * fq;
;         f32x4 gv[2][2];
; #pragma unroll
;         for (int bj = 0; bj < 2; ++bj)
; #pragma unroll
;             for (int n = 0; n < 2; ++n) gv[bj][n] = *(const f32x4*)(gate + col0 + bj * HALF + n * 16) * coef;
; #pragma unroll
;         for (int ai = 0; ai < 2; ++ai)
; #pragma unroll
;             for (int m = 0; m < 4; ++m) {
;                 const int row = u.pm * BM + ai * HALF + wr * 64 + m * 16 + fr;
;                 const float* s = row < MX_ ? src_main + (size_t)row * D_ : src_ctx + (size_t)(row - MX_) * D_;
;                 float* d = row < MX_ ? dst_main + (size_t)row * D_ : dst_ctx + (size_t)(row - MX_) * D_;
; #pragma unroll
;                 for (int bj = 0; bj < 2; ++bj)
; #pragma unroll
;                     for (int n = 0; n < 2; ++n) { const int off = col0 + bj * HALF + n * 16; const f32x4 xo = *(const f32x4*)(s + off); *(f32x4*)(d + off) = xo + gv[bj][n] * acc[ai][bj][m][n]; }
.LBB0_1346:
	s_cmpk_lt_i32 s6, 0x80
	s_cselect_b32 s8, s64, 0x4800
	s_cmp_gt_i32 s6, 63
	s_cselect_b32 s8, s8, 0
	s_lshl_b32 s8, s8, 2
	s_add_u32 s8, s56, s8
	s_addc_u32 s9, s57, 0
	v_lshl_add_u32 v156, s6, 8, v158
	v_lshl_or_b32 v157, s7, 8, v160
	v_lshlrev_b32_e32 v201, 2, v157
	v_lshl_add_u32 v240, v156, 12, v201
	global_load_dwordx4 v[224:227], v201, s[8:9]
	global_load_dwordx4 v[228:231], v201, s[8:9] offset:64
	global_load_dwordx4 v[232:235], v201, s[8:9] offset:512
	global_load_dwordx4 v[236:239], v201, s[8:9] offset:576
	v_add_u32_e32 v241, 0x10000, v240
	v_add_u32_e32 v242, 0x20000, v240
	v_add_u32_e32 v243, 0x30000, v240
	v_add_u32_e32 v244, 0x80000, v240
	v_add_u32_e32 v245, 0x90000, v240
	v_add_u32_e32 v246, 0xa0000, v240
	v_add_u32_e32 v247, 0xb0000, v240
	global_load_dwordx4 v[140:143], v240, s[16:17]
	global_load_dwordx4 v[144:147], v240, s[16:17] offset:64
	global_load_dwordx4 v[148:151], v240, s[16:17] offset:512
	global_load_dwordx4 v[152:155], v240, s[16:17] offset:576
	global_load_dwordx4 v[164:167], v241, s[16:17]
	global_load_dwordx4 v[168:171], v241, s[16:17] offset:64
	global_load_dwordx4 v[172:175], v241, s[16:17] offset:512
	global_load_dwordx4 v[176:179], v241, s[16:17] offset:576
	global_load_dwordx4 v[180:183], v242, s[16:17]
	global_load_dwordx4 v[184:187], v242, s[16:17] offset:64
	global_load_dwordx4 v[188:191], v242, s[16:17] offset:512
	global_load_dwordx4 v[192:195], v242, s[16:17] offset:576
	global_load_dwordx4 v[196:199], v243, s[16:17]
	global_load_dwordx4 v[212:215], v243, s[16:17] offset:64
	global_load_dwordx4 v[216:219], v243, s[16:17] offset:512
	global_load_dwordx4 v[220:223], v243, s[16:17] offset:576
	s_waitcnt vmcnt(16)
	v_pk_mul_f32 v[224:225], v[224:225], 0.5 op_sel_hi:[1,0]
	v_pk_mul_f32 v[226:227], v[226:227], 0.5 op_sel_hi:[1,0]
	v_pk_mul_f32 v[228:229], v[228:229], 0.5 op_sel_hi:[1,0]
	v_pk_mul_f32 v[230:231], v[230:231], 0.5 op_sel_hi:[1,0]
	v_pk_mul_f32 v[232:233], v[232:233], 0.5 op_sel_hi:[1,0]
	v_pk_mul_f32 v[234:235], v[234:235], 0.5 op_sel_hi:[1,0]
	v_pk_mul_f32 v[236:237], v[236:237], 0.5 op_sel_hi:[1,0]
	v_pk_mul_f32 v[238:239], v[238:239], 0.5 op_sel_hi:[1,0]
	s_waitcnt vmcnt(15)
	v_pk_fma_f32 v[124:125], v[124:125], v[224:225], v[140:141]
	v_pk_fma_f32 v[126:127], v[126:127], v[226:227], v[142:143]
	s_waitcnt vmcnt(14)
	v_pk_fma_f32 v[120:121], v[120:121], v[228:229], v[144:145]
	v_pk_fma_f32 v[122:123], v[122:123], v[230:231], v[146:147]
	s_waitcnt vmcnt(13)
	v_pk_fma_f32 v[116:117], v[116:117], v[232:233], v[148:149]
	v_pk_fma_f32 v[118:119], v[118:119], v[234:235], v[150:151]
	s_waitcnt vmcnt(12)
	v_pk_fma_f32 v[112:113], v[112:113], v[236:237], v[152:153]
	v_pk_fma_f32 v[114:115], v[114:115], v[238:239], v[154:155]
	global_store_dwordx4 v240, v[124:127], s[16:17]
	global_store_dwordx4 v240, v[120:123], s[16:17] offset:64
	global_store_dwordx4 v240, v[116:119], s[16:17] offset:512
	global_store_dwordx4 v240, v[112:115], s[16:17] offset:576
	global_load_dwordx4 v[140:143], v244, s[16:17]
	global_load_dwordx4 v[144:147], v244, s[16:17] offset:64
	global_load_dwordx4 v[148:151], v244, s[16:17] offset:512
	global_load_dwordx4 v[152:155], v244, s[16:17] offset:576
	s_waitcnt vmcnt(19)
	v_pk_fma_f32 v[108:109], v[108:109], v[224:225], v[164:165]
	v_pk_fma_f32 v[110:111], v[110:111], v[226:227], v[166:167]
	s_waitcnt vmcnt(18)
	v_pk_fma_f32 v[104:105], v[104:105], v[228:229], v[168:169]
	v_pk_fma_f32 v[106:107], v[106:107], v[230:231], v[170:171]
	s_waitcnt vmcnt(17)
	v_pk_fma_f32 v[100:101], v[100:101], v[232:233], v[172:173]
	v_pk_fma_f32 v[102:103], v[102:103], v[234:235], v[174:175]
	s_waitcnt vmcnt(16)
	v_pk_fma_f32 v[96:97], v[96:97], v[236:237], v[176:177]
	v_pk_fma_f32 v[98:99], v[98:99], v[238:239], v[178:179]
	global_store_dwordx4 v241, v[108:111], s[16:17]
	global_store_dwordx4 v241, v[104:107], s[16:17] offset:64
	global_store_dwordx4 v241, v[100:103], s[16:17] offset:512
	global_store_dwordx4 v241, v[96:99], s[16:17] offset:576
	global_load_dwordx4 v[164:167], v245, s[16:17]
	global_load_dwordx4 v[168:171], v245, s[16:17] offset:64
	global_load_dwordx4 v[172:175], v245, s[16:17] offset:512
	global_load_dwordx4 v[176:179], v245, s[16:17] offset:576
	s_waitcnt vmcnt(23)
	v_pk_fma_f32 v[92:93], v[92:93], v[224:225], v[180:181]
	v_pk_fma_f32 v[94:95], v[94:95], v[226:227], v[182:183]
	s_waitcnt vmcnt(22)
	v_pk_fma_f32 v[88:89], v[88:89], v[228:229], v[184:185]
	v_pk_fma_f32 v[90:91], v[90:91], v[230:231], v[186:187]
	s_waitcnt vmcnt(21)
	v_pk_fma_f32 v[84:85], v[84:85], v[232:233], v[188:189]
	v_pk_fma_f32 v[86:87], v[86:87], v[234:235], v[190:191]
	s_waitcnt vmcnt(20)
; #define PG8_BAR __builtin_amdgcn_s_barrier()
;     __device__ __forceinline__ void operator()(const f32x4 (&acc)[2][2][4][2], const Unit& u, int wr, int wc, int fr, int fq) const {
;     ...
;             for (int m = 0; m < 4; ++m) {
;                 const int row = u.pm * BM + ai * HALF + wr * 64 + m * 16 + fr;
;                 const float* s = row < MX_ ? src_main + (size_t)row * D_ : src_ctx + (size_t)(row - MX_) * D_;
;                 float* d = row < MX_ ? dst_main + (size_t)row * D_ : dst_ctx + (size_t)(row - MX_) * D_;
; #pragma unroll
;                 for (int bj = 0; bj < 2; ++bj)
; #pragma unroll
;                     for (int n = 0; n < 2; ++n) { const int off = col0 + bj * HALF + n * 16; const f32x4 xo = *(const f32x4*)(s + off); *(f32x4*)(d + off) = xo + gv[bj][n] * acc[ai][bj][m][n]; }
;     ...
;         if (!has_next) break;
; #pragma unroll
;         for (int a = 0; a < 2; ++a)
; #pragma unroll
;             for (int b = 0; b < 2; ++b)
; #pragma unroll
;                 for (int m = 0; m < 4; ++m)
; #pragma unroll
;                     for (int n = 0; n < 2; ++n) acc[a][b][m][n] = (f32x4){0.f, 0.f, 0.f, 0.f};
;         cur = nxt; cA = nA; cB = nB; ++ui;
;         if constexpr (ALIGN_EPI) { if (wr == 1) PG8_BAR; }
	v_pk_fma_f32 v[80:81], v[80:81], v[236:237], v[192:193]
	v_pk_fma_f32 v[82:83], v[82:83], v[238:239], v[194:195]
	global_store_dwordx4 v242, v[92:95], s[16:17]
	global_store_dwordx4 v242, v[88:91], s[16:17] offset:64
	global_store_dwordx4 v242, v[84:87], s[16:17] offset:512
	global_store_dwordx4 v242, v[80:83], s[16:17] offset:576
	global_load_dwordx4 v[180:183], v246, s[16:17]
	global_load_dwordx4 v[184:187], v246, s[16:17] offset:64
	global_load_dwordx4 v[188:191], v246, s[16:17] offset:512
	global_load_dwordx4 v[192:195], v246, s[16:17] offset:576
	s_waitcnt vmcnt(27)
	v_pk_fma_f32 v[76:77], v[76:77], v[224:225], v[196:197]
	v_pk_fma_f32 v[78:79], v[78:79], v[226:227], v[198:199]
	s_waitcnt vmcnt(26)
	v_pk_fma_f32 v[72:73], v[72:73], v[228:229], v[212:213]
	v_pk_fma_f32 v[74:75], v[74:75], v[230:231], v[214:215]
	s_waitcnt vmcnt(25)
	v_pk_fma_f32 v[68:69], v[68:69], v[232:233], v[216:217]
	v_pk_fma_f32 v[70:71], v[70:71], v[234:235], v[218:219]
	s_waitcnt vmcnt(24)
	v_pk_fma_f32 v[64:65], v[64:65], v[236:237], v[220:221]
	v_pk_fma_f32 v[66:67], v[66:67], v[238:239], v[222:223]
	global_store_dwordx4 v243, v[76:79], s[16:17]
	global_store_dwordx4 v243, v[72:75], s[16:17] offset:64
	global_store_dwordx4 v243, v[68:71], s[16:17] offset:512
	global_store_dwordx4 v243, v[64:67], s[16:17] offset:576
	global_load_dwordx4 v[196:199], v247, s[16:17]
	global_load_dwordx4 v[212:215], v247, s[16:17] offset:64
	global_load_dwordx4 v[216:219], v247, s[16:17] offset:512
	global_load_dwordx4 v[220:223], v247, s[16:17] offset:576
	s_waitcnt vmcnt(27)
	v_pk_fma_f32 v[60:61], v[60:61], v[224:225], v[140:141]
	v_pk_fma_f32 v[62:63], v[62:63], v[226:227], v[142:143]
	s_waitcnt vmcnt(26)
	v_pk_fma_f32 v[56:57], v[56:57], v[228:229], v[144:145]
	v_pk_fma_f32 v[58:59], v[58:59], v[230:231], v[146:147]
	s_waitcnt vmcnt(25)
	v_pk_fma_f32 v[52:53], v[52:53], v[232:233], v[148:149]
	v_pk_fma_f32 v[54:55], v[54:55], v[234:235], v[150:151]
	s_waitcnt vmcnt(24)
	v_pk_fma_f32 v[48:49], v[48:49], v[236:237], v[152:153]
	v_pk_fma_f32 v[50:51], v[50:51], v[238:239], v[154:155]
	global_store_dwordx4 v244, v[60:63], s[16:17]
	global_store_dwordx4 v244, v[56:59], s[16:17] offset:64
	global_store_dwordx4 v244, v[52:55], s[16:17] offset:512
	global_store_dwordx4 v244, v[48:51], s[16:17] offset:576
	s_waitcnt vmcnt(23)
	v_pk_fma_f32 v[44:45], v[44:45], v[224:225], v[164:165]
	v_pk_fma_f32 v[46:47], v[46:47], v[226:227], v[166:167]
	s_waitcnt vmcnt(22)
	v_pk_fma_f32 v[40:41], v[40:41], v[228:229], v[168:169]
	v_pk_fma_f32 v[42:43], v[42:43], v[230:231], v[170:171]
	s_waitcnt vmcnt(21)
	v_pk_fma_f32 v[36:37], v[36:37], v[232:233], v[172:173]
	v_pk_fma_f32 v[38:39], v[38:39], v[234:235], v[174:175]
	s_waitcnt vmcnt(20)
	v_pk_fma_f32 v[32:33], v[32:33], v[236:237], v[176:177]
	v_pk_fma_f32 v[34:35], v[34:35], v[238:239], v[178:179]
	global_store_dwordx4 v245, v[44:47], s[16:17]
	global_store_dwordx4 v245, v[40:43], s[16:17] offset:64
	global_store_dwordx4 v245, v[36:39], s[16:17] offset:512
	global_store_dwordx4 v245, v[32:35], s[16:17] offset:576
	s_waitcnt vmcnt(19)
	v_pk_fma_f32 v[28:29], v[28:29], v[224:225], v[180:181]
	v_pk_fma_f32 v[30:31], v[30:31], v[226:227], v[182:183]
	s_waitcnt vmcnt(18)
	v_pk_fma_f32 v[24:25], v[24:25], v[228:229], v[184:185]
	v_pk_fma_f32 v[26:27], v[26:27], v[230:231], v[186:187]
	s_waitcnt vmcnt(17)
	v_pk_fma_f32 v[20:21], v[20:21], v[232:233], v[188:189]
	v_pk_fma_f32 v[22:23], v[22:23], v[234:235], v[190:191]
	s_waitcnt vmcnt(16)
	v_pk_fma_f32 v[16:17], v[16:17], v[236:237], v[192:193]
	v_pk_fma_f32 v[18:19], v[18:19], v[238:239], v[194:195]
	global_store_dwordx4 v246, v[28:31], s[16:17]
	global_store_dwordx4 v246, v[24:27], s[16:17] offset:64
	global_store_dwordx4 v246, v[20:23], s[16:17] offset:512
	global_store_dwordx4 v246, v[16:19], s[16:17] offset:576
	s_waitcnt vmcnt(15)
	v_pk_fma_f32 v[12:13], v[12:13], v[224:225], v[196:197]
	v_pk_fma_f32 v[14:15], v[14:15], v[226:227], v[198:199]
	s_waitcnt vmcnt(14)
	v_pk_fma_f32 v[8:9], v[8:9], v[228:229], v[212:213]
	v_pk_fma_f32 v[10:11], v[10:11], v[230:231], v[214:215]
	s_waitcnt vmcnt(13)
	v_pk_fma_f32 v[4:5], v[4:5], v[232:233], v[216:217]
	v_pk_fma_f32 v[6:7], v[6:7], v[234:235], v[218:219]
	s_waitcnt vmcnt(12)
	v_pk_fma_f32 v[0:1], v[0:1], v[236:237], v[220:221]
	v_pk_fma_f32 v[2:3], v[2:3], v[238:239], v[222:223]
	global_store_dwordx4 v247, v[12:15], s[16:17]
	global_store_dwordx4 v247, v[8:11], s[16:17] offset:64
	global_store_dwordx4 v247, v[4:7], s[16:17] offset:512
	global_store_dwordx4 v247, v[0:3], s[16:17] offset:576
	s_and_b64 vcc, exec, s[12:13]
	s_mov_b64 s[12:13], -1
	s_cbranch_vccnz .LBB0_1331
	s_andn2_b64 vcc, exec, s[18:19]
	s_cbranch_vccnz .LBB0_1330
	s_barrier
	s_branch .LBB0_1330

;     __device__ __forceinline__ void operator()(const f32x4 (&acc)[2][2][4][2], const Unit& u, int wr, int wc, int fr, int fq) const {
;         const int cond = u.pm < 64 ? 0 : (u.pm < 128 ? 1 : 2);
;         const float* gate = gate_l + cond * 9216;
;         const int col0 = u.pn * BM + wc * 32 + 4 * fq;
;         f32x4 gv[2][2];
; #pragma unroll
;         for (int bj = 0; bj < 2; ++bj)
; #pragma unroll
;             for (int n = 0; n < 2; ++n) gv[bj][n] = *(const f32x4*)(gate + col0 + bj * HALF + n * 16) * coef;
; #pragma unroll
;         for (int ai = 0; ai < 2; ++ai)
; #pragma unroll
;             for (int m = 0; m < 4; ++m) {
;                 const int row = u.pm * BM + ai * HALF + wr * 64 + m * 16 + fr;
;                 const float* s = row < MX_ ? src_main + (size_t)row * D_ : src_ctx + (size_t)(row - MX_) * D_;
;                 float* d = row < MX_ ? dst_main + (size_t)row * D_ : dst_ctx + (size_t)(row - MX_) * D_;
; #pragma unroll
;                 for (int bj = 0; bj < 2; ++bj)
; #pragma unroll
;                     for (int n = 0; n < 2; ++n) { const int off = col0 + bj * HALF + n * 16; const f32x4 xo = *(const f32x4*)(s + off); *(f32x4*)(d + off) = xo + gv[bj][n] * acc[ai][bj][m][n]; }
.LBB0_1566:
	s_cmpk_lt_i32 s6, 0x80
	s_cselect_b32 s8, s62, 0x4800
	s_cmp_gt_i32 s6, 63
	s_cselect_b32 s8, s8, 0
	s_lshl_b32 s8, s8, 2
	s_add_u32 s8, s54, s8
	s_addc_u32 s9, s55, 0
	v_lshl_add_u32 v156, s6, 8, v158
	v_lshl_or_b32 v157, s7, 8, v160
	v_lshlrev_b32_e32 v201, 2, v157
	v_lshl_add_u32 v240, v156, 12, v201
	global_load_dwordx4 v[224:227], v201, s[8:9]
	global_load_dwordx4 v[228:231], v201, s[8:9] offset:64
	global_load_dwordx4 v[232:235], v201, s[8:9] offset:512
	global_load_dwordx4 v[236:239], v201, s[8:9] offset:576
	v_add_u32_e32 v241, 0x10000, v240
	v_add_u32_e32 v242, 0x20000, v240
	v_add_u32_e32 v243, 0x30000, v240
	v_add_u32_e32 v244, 0x80000, v240
	v_add_u32_e32 v245, 0x90000, v240
	v_add_u32_e32 v246, 0xa0000, v240
	v_add_u32_e32 v247, 0xb0000, v240
	global_load_dwordx4 v[140:143], v240, s[14:15]
	global_load_dwordx4 v[144:147], v240, s[14:15] offset:64
	global_load_dwordx4 v[148:151], v240, s[14:15] offset:512
	global_load_dwordx4 v[152:155], v240, s[14:15] offset:576
	global_load_dwordx4 v[164:167], v241, s[14:15]
	global_load_dwordx4 v[168:171], v241, s[14:15] offset:64
	global_load_dwordx4 v[172:175], v241, s[14:15] offset:512
	global_load_dwordx4 v[176:179], v241, s[14:15] offset:576
	global_load_dwordx4 v[180:183], v242, s[14:15]
	global_load_dwordx4 v[184:187], v242, s[14:15] offset:64
	global_load_dwordx4 v[188:191], v242, s[14:15] offset:512
	global_load_dwordx4 v[192:195], v242, s[14:15] offset:576
	global_load_dwordx4 v[196:199], v243, s[14:15]
	global_load_dwordx4 v[212:215], v243, s[14:15] offset:64
	global_load_dwordx4 v[216:219], v243, s[14:15] offset:512
	global_load_dwordx4 v[220:223], v243, s[14:15] offset:576
	s_waitcnt vmcnt(16)
	v_pk_mul_f32 v[224:225], v[224:225], 0.5 op_sel_hi:[1,0]
	v_pk_mul_f32 v[226:227], v[226:227], 0.5 op_sel_hi:[1,0]
	v_pk_mul_f32 v[228:229], v[228:229], 0.5 op_sel_hi:[1,0]
	v_pk_mul_f32 v[230:231], v[230:231], 0.5 op_sel_hi:[1,0]
	v_pk_mul_f32 v[232:233], v[232:233], 0.5 op_sel_hi:[1,0]
	v_pk_mul_f32 v[234:235], v[234:235], 0.5 op_sel_hi:[1,0]
	v_pk_mul_f32 v[236:237], v[236:237], 0.5 op_sel_hi:[1,0]
	v_pk_mul_f32 v[238:239], v[238:239], 0.5 op_sel_hi:[1,0]
	s_waitcnt vmcnt(15)
	v_pk_fma_f32 v[124:125], v[124:125], v[224:225], v[140:141]
	v_pk_fma_f32 v[126:127], v[126:127], v[226:227], v[142:143]
	s_waitcnt vmcnt(14)
	v_pk_fma_f32 v[120:121], v[120:121], v[228:229], v[144:145]
	v_pk_fma_f32 v[122:123], v[122:123], v[230:231], v[146:147]
	s_waitcnt vmcnt(13)
	v_pk_fma_f32 v[116:117], v[116:117], v[232:233], v[148:149]
	v_pk_fma_f32 v[118:119], v[118:119], v[234:235], v[150:151]
	s_waitcnt vmcnt(12)
	v_pk_fma_f32 v[112:113], v[112:113], v[236:237], v[152:153]
	v_pk_fma_f32 v[114:115], v[114:115], v[238:239], v[154:155]
	global_store_dwordx4 v240, v[124:127], s[14:15]
	global_store_dwordx4 v240, v[120:123], s[14:15] offset:64
	global_store_dwordx4 v240, v[116:119], s[14:15] offset:512
	global_store_dwordx4 v240, v[112:115], s[14:15] offset:576
	global_load_dwordx4 v[140:143], v244, s[14:15]
	global_load_dwordx4 v[144:147], v244, s[14:15] offset:64
	global_load_dwordx4 v[148:151], v244, s[14:15] offset:512
	global_load_dwordx4 v[152:155], v244, s[14:15] offset:576
	s_waitcnt vmcnt(19)
	v_pk_fma_f32 v[108:109], v[108:109], v[224:225], v[164:165]
	v_pk_fma_f32 v[110:111], v[110:111], v[226:227], v[166:167]
	s_waitcnt vmcnt(18)
	v_pk_fma_f32 v[104:105], v[104:105], v[228:229], v[168:169]
	v_pk_fma_f32 v[106:107], v[106:107], v[230:231], v[170:171]
	s_waitcnt vmcnt(17)
	v_pk_fma_f32 v[100:101], v[100:101], v[232:233], v[172:173]
	v_pk_fma_f32 v[102:103], v[102:103], v[234:235], v[174:175]
	s_waitcnt vmcnt(16)
	v_pk_fma_f32 v[96:97], v[96:97], v[236:237], v[176:177]
	v_pk_fma_f32 v[98:99], v[98:99], v[238:239], v[178:179]
	global_store_dwordx4 v241, v[108:111], s[14:15]
	global_store_dwordx4 v241, v[104:107], s[14:15] offset:64
	global_store_dwordx4 v241, v[100:103], s[14:15] offset:512
	global_store_dwordx4 v241, v[96:99], s[14:15] offset:576
	global_load_dwordx4 v[164:167], v245, s[14:15]
	global_load_dwordx4 v[168:171], v245, s[14:15] offset:64
	global_load_dwordx4 v[172:175], v245, s[14:15] offset:512
	global_load_dwordx4 v[176:179], v245, s[14:15] offset:576
	s_waitcnt vmcnt(23)
	v_pk_fma_f32 v[92:93], v[92:93], v[224:225], v[180:181]
	v_pk_fma_f32 v[94:95], v[94:95], v[226:227], v[182:183]
	s_waitcnt vmcnt(22)
	v_pk_fma_f32 v[88:89], v[88:89], v[228:229], v[184:185]
	v_pk_fma_f32 v[90:91], v[90:91], v[230:231], v[186:187]
	s_waitcnt vmcnt(21)
	v_pk_fma_f32 v[84:85], v[84:85], v[232:233], v[188:189]
	v_pk_fma_f32 v[86:87], v[86:87], v[234:235], v[190:191]
	s_waitcnt vmcnt(20)
; #define PG8_BAR __builtin_amdgcn_s_barrier()
;     __device__ __forceinline__ void operator()(const f32x4 (&acc)[2][2][4][2], const Unit& u, int wr, int wc, int fr, int fq) const {
;     ...
;             for (int m = 0; m < 4; ++m) {
;                 const int row = u.pm * BM + ai * HALF + wr * 64 + m * 16 + fr;
;                 const float* s = row < MX_ ? src_main + (size_t)row * D_ : src_ctx + (size_t)(row - MX_) * D_;
;                 float* d = row < MX_ ? dst_main + (size_t)row * D_ : dst_ctx + (size_t)(row - MX_) * D_;
; #pragma unroll
;                 for (int bj = 0; bj < 2; ++bj)
; #pragma unroll
;                     for (int n = 0; n < 2; ++n) { const int off = col0 + bj * HALF + n * 16; const f32x4 xo = *(const f32x4*)(s + off); *(f32x4*)(d + off) = xo + gv[bj][n] * acc[ai][bj][m][n]; }
;     ...
;         if (!has_next) break;
; #pragma unroll
;         for (int a = 0; a < 2; ++a)
; #pragma unroll
;             for (int b = 0; b < 2; ++b)
; #pragma unroll
;                 for (int m = 0; m < 4; ++m)
; #pragma unroll
;                     for (int n = 0; n < 2; ++n) acc[a][b][m][n] = (f32x4){0.f, 0.f, 0.f, 0.f};
;         cur = nxt; cA = nA; cB = nB; ++ui;
;         if constexpr (ALIGN_EPI) { if (wr == 1) PG8_BAR; }
	v_pk_fma_f32 v[80:81], v[80:81], v[236:237], v[192:193]
	v_pk_fma_f32 v[82:83], v[82:83], v[238:239], v[194:195]
	global_store_dwordx4 v242, v[92:95], s[14:15]
	global_store_dwordx4 v242, v[88:91], s[14:15] offset:64
	global_store_dwordx4 v242, v[84:87], s[14:15] offset:512
	global_store_dwordx4 v242, v[80:83], s[14:15] offset:576
	global_load_dwordx4 v[180:183], v246, s[14:15]
	global_load_dwordx4 v[184:187], v246, s[14:15] offset:64
	global_load_dwordx4 v[188:191], v246, s[14:15] offset:512
	global_load_dwordx4 v[192:195], v246, s[14:15] offset:576
	s_waitcnt vmcnt(27)
	v_pk_fma_f32 v[76:77], v[76:77], v[224:225], v[196:197]
	v_pk_fma_f32 v[78:79], v[78:79], v[226:227], v[198:199]
	s_waitcnt vmcnt(26)
	v_pk_fma_f32 v[72:73], v[72:73], v[228:229], v[212:213]
	v_pk_fma_f32 v[74:75], v[74:75], v[230:231], v[214:215]
	s_waitcnt vmcnt(25)
	v_pk_fma_f32 v[68:69], v[68:69], v[232:233], v[216:217]
	v_pk_fma_f32 v[70:71], v[70:71], v[234:235], v[218:219]
	s_waitcnt vmcnt(24)
	v_pk_fma_f32 v[64:65], v[64:65], v[236:237], v[220:221]
	v_pk_fma_f32 v[66:67], v[66:67], v[238:239], v[222:223]
	global_store_dwordx4 v243, v[76:79], s[14:15]
	global_store_dwordx4 v243, v[72:75], s[14:15] offset:64
	global_store_dwordx4 v243, v[68:71], s[14:15] offset:512
	global_store_dwordx4 v243, v[64:67], s[14:15] offset:576
	global_load_dwordx4 v[196:199], v247, s[14:15]
	global_load_dwordx4 v[212:215], v247, s[14:15] offset:64
	global_load_dwordx4 v[216:219], v247, s[14:15] offset:512
	global_load_dwordx4 v[220:223], v247, s[14:15] offset:576
	s_waitcnt vmcnt(27)
	v_pk_fma_f32 v[60:61], v[60:61], v[224:225], v[140:141]
	v_pk_fma_f32 v[62:63], v[62:63], v[226:227], v[142:143]
	s_waitcnt vmcnt(26)
	v_pk_fma_f32 v[56:57], v[56:57], v[228:229], v[144:145]
	v_pk_fma_f32 v[58:59], v[58:59], v[230:231], v[146:147]
	s_waitcnt vmcnt(25)
	v_pk_fma_f32 v[52:53], v[52:53], v[232:233], v[148:149]
	v_pk_fma_f32 v[54:55], v[54:55], v[234:235], v[150:151]
	s_waitcnt vmcnt(24)
	v_pk_fma_f32 v[48:49], v[48:49], v[236:237], v[152:153]
	v_pk_fma_f32 v[50:51], v[50:51], v[238:239], v[154:155]
	global_store_dwordx4 v244, v[60:63], s[14:15]
	global_store_dwordx4 v244, v[56:59], s[14:15] offset:64
	global_store_dwordx4 v244, v[52:55], s[14:15] offset:512
	global_store_dwordx4 v244, v[48:51], s[14:15] offset:576
	s_waitcnt vmcnt(23)
	v_pk_fma_f32 v[44:45], v[44:45], v[224:225], v[164:165]
	v_pk_fma_f32 v[46:47], v[46:47], v[226:227], v[166:167]
	s_waitcnt vmcnt(22)
	v_pk_fma_f32 v[40:41], v[40:41], v[228:229], v[168:169]
	v_pk_fma_f32 v[42:43], v[42:43], v[230:231], v[170:171]
	s_waitcnt vmcnt(21)
	v_pk_fma_f32 v[36:37], v[36:37], v[232:233], v[172:173]
	v_pk_fma_f32 v[38:39], v[38:39], v[234:235], v[174:175]
	s_waitcnt vmcnt(20)
	v_pk_fma_f32 v[32:33], v[32:33], v[236:237], v[176:177]
	v_pk_fma_f32 v[34:35], v[34:35], v[238:239], v[178:179]
	global_store_dwordx4 v245, v[44:47], s[14:15]
	global_store_dwordx4 v245, v[40:43], s[14:15] offset:64
	global_store_dwordx4 v245, v[36:39], s[14:15] offset:512
	global_store_dwordx4 v245, v[32:35], s[14:15] offset:576
	s_waitcnt vmcnt(19)
	v_pk_fma_f32 v[28:29], v[28:29], v[224:225], v[180:181]
	v_pk_fma_f32 v[30:31], v[30:31], v[226:227], v[182:183]
	s_waitcnt vmcnt(18)
	v_pk_fma_f32 v[24:25], v[24:25], v[228:229], v[184:185]
	v_pk_fma_f32 v[26:27], v[26:27], v[230:231], v[186:187]
	s_waitcnt vmcnt(17)
	v_pk_fma_f32 v[20:21], v[20:21], v[232:233], v[188:189]
	v_pk_fma_f32 v[22:23], v[22:23], v[234:235], v[190:191]
	s_waitcnt vmcnt(16)
	v_pk_fma_f32 v[16:17], v[16:17], v[236:237], v[192:193]
	v_pk_fma_f32 v[18:19], v[18:19], v[238:239], v[194:195]
	global_store_dwordx4 v246, v[28:31], s[14:15]
	global_store_dwordx4 v246, v[24:27], s[14:15] offset:64
	global_store_dwordx4 v246, v[20:23], s[14:15] offset:512
	global_store_dwordx4 v246, v[16:19], s[14:15] offset:576
	s_waitcnt vmcnt(15)
	v_pk_fma_f32 v[12:13], v[12:13], v[224:225], v[196:197]
	v_pk_fma_f32 v[14:15], v[14:15], v[226:227], v[198:199]
	s_waitcnt vmcnt(14)
	v_pk_fma_f32 v[8:9], v[8:9], v[228:229], v[212:213]
	v_pk_fma_f32 v[10:11], v[10:11], v[230:231], v[214:215]
	s_waitcnt vmcnt(13)
	v_pk_fma_f32 v[4:5], v[4:5], v[232:233], v[216:217]
	v_pk_fma_f32 v[6:7], v[6:7], v[234:235], v[218:219]
	s_waitcnt vmcnt(12)
	v_pk_fma_f32 v[0:1], v[0:1], v[236:237], v[220:221]
	v_pk_fma_f32 v[2:3], v[2:3], v[238:239], v[222:223]
	global_store_dwordx4 v247, v[12:15], s[14:15]
	global_store_dwordx4 v247, v[8:11], s[14:15] offset:64
	global_store_dwordx4 v247, v[4:7], s[14:15] offset:512
	global_store_dwordx4 v247, v[0:3], s[14:15] offset:576
	s_and_b64 vcc, exec, s[10:11]
	s_mov_b64 s[10:11], -1
	s_cbranch_vccnz .LBB0_1551
	s_andn2_b64 vcc, exec, s[16:17]
	s_cbranch_vccnz .LBB0_1550
	s_barrier
	s_branch .LBB0_1550

;     __device__ __forceinline__ void operator()(const f32x4 (&acc)[2][2][4][2], const Unit& u, int wr, int wc, int fr, int fq) const {
;         const int cond = u.pm < 64 ? 0 : (u.pm < 128 ? 1 : 2);
;         const float* gate = gate_l + cond * 9216;
;         const int col0 = u.pn * BM + wc * 32 + 4 * fq;
;         f32x4 gv[2][2];
; #pragma unroll
;         for (int bj = 0; bj < 2; ++bj)
; #pragma unroll
;             for (int n = 0; n < 2; ++n) gv[bj][n] = *(const f32x4*)(gate + col0 + bj * HALF + n * 16) * coef;
; #pragma unroll
;         for (int ai = 0; ai < 2; ++ai)
; #pragma unroll
;             for (int m = 0; m < 4; ++m) {
;                 const int row = u.pm * BM + ai * HALF + wr * 64 + m * 16 + fr;
;                 const float* s = row < MX_ ? src_main + (size_t)row * D_ : src_ctx + (size_t)(row - MX_) * D_;
;                 float* d = row < MX_ ? dst_main + (size_t)row * D_ : dst_ctx + (size_t)(row - MX_) * D_;
; #pragma unroll
;                 for (int bj = 0; bj < 2; ++bj)
; #pragma unroll
;                     for (int n = 0; n < 2; ++n) { const int off = col0 + bj * HALF + n * 16; const f32x4 xo = *(const f32x4*)(s + off); *(f32x4*)(d + off) = xo + gv[bj][n] * acc[ai][bj][m][n]; }
.LBB0_2337:
	s_cmpk_lt_i32 s26, 0x80
	s_cselect_b32 s17, s63, 0x4800
	s_cmp_gt_i32 s26, 63
	s_cselect_b32 s17, s17, 0
	s_lshl_b32 s17, s17, 2
	s_add_u32 s34, s55, s17
	s_addc_u32 s35, s56, 0
	v_lshl_add_u32 v156, s26, 8, v158
	v_lshl_or_b32 v157, s64, 8, v160
	v_lshlrev_b32_e32 v200, 2, v157
	v_lshl_add_u32 v201, v156, 12, v200
	global_load_dwordx4 v[220:223], v200, s[34:35]
	global_load_dwordx4 v[224:227], v200, s[34:35] offset:64
	global_load_dwordx4 v[228:231], v200, s[34:35] offset:512
	global_load_dwordx4 v[232:235], v200, s[34:35] offset:576
	v_add_u32_e32 v205, 0x10000, v201
	v_add_u32_e32 v207, 0x20000, v201
	v_add_u32_e32 v236, 0x30000, v201
	v_add_u32_e32 v237, 0x80000, v201
	v_add_u32_e32 v238, 0x90000, v201
	v_add_u32_e32 v239, 0xa0000, v201
	v_add_u32_e32 v240, 0xb0000, v201
	global_load_dwordx4 v[128:131], v201, s[8:9]
	global_load_dwordx4 v[132:135], v201, s[8:9] offset:64
	global_load_dwordx4 v[136:139], v201, s[8:9] offset:512
	global_load_dwordx4 v[140:143], v201, s[8:9] offset:576
	global_load_dwordx4 v[164:167], v205, s[8:9]
	global_load_dwordx4 v[168:171], v205, s[8:9] offset:64
	global_load_dwordx4 v[172:175], v205, s[8:9] offset:512
	global_load_dwordx4 v[176:179], v205, s[8:9] offset:576
	global_load_dwordx4 v[180:183], v207, s[8:9]
	global_load_dwordx4 v[184:187], v207, s[8:9] offset:64
	global_load_dwordx4 v[188:191], v207, s[8:9] offset:512
	global_load_dwordx4 v[192:195], v207, s[8:9] offset:576
	global_load_dwordx4 v[196:199], v236, s[8:9]
	global_load_dwordx4 v[208:211], v236, s[8:9] offset:64
	global_load_dwordx4 v[212:215], v236, s[8:9] offset:512
	global_load_dwordx4 v[216:219], v236, s[8:9] offset:576
	s_waitcnt vmcnt(16)
	s_waitcnt vmcnt(15)
	v_pk_fma_f32 v[124:125], v[124:125], v[220:221], v[128:129]
	v_pk_fma_f32 v[126:127], v[126:127], v[222:223], v[130:131]
	s_waitcnt vmcnt(14)
	v_pk_fma_f32 v[120:121], v[120:121], v[224:225], v[132:133]
	v_pk_fma_f32 v[122:123], v[122:123], v[226:227], v[134:135]
	s_waitcnt vmcnt(13)
	v_pk_fma_f32 v[116:117], v[116:117], v[228:229], v[136:137]
	v_pk_fma_f32 v[118:119], v[118:119], v[230:231], v[138:139]
	s_waitcnt vmcnt(12)
	v_pk_fma_f32 v[112:113], v[112:113], v[232:233], v[140:141]
	v_pk_fma_f32 v[114:115], v[114:115], v[234:235], v[142:143]
	global_store_dwordx4 v201, v[124:127], s[8:9]
	global_store_dwordx4 v201, v[120:123], s[8:9] offset:64
	global_store_dwordx4 v201, v[116:119], s[8:9] offset:512
	global_store_dwordx4 v201, v[112:115], s[8:9] offset:576
	global_load_dwordx4 v[128:131], v237, s[8:9]
	global_load_dwordx4 v[132:135], v237, s[8:9] offset:64
	global_load_dwordx4 v[136:139], v237, s[8:9] offset:512
	global_load_dwordx4 v[140:143], v237, s[8:9] offset:576
	s_waitcnt vmcnt(19)
	v_pk_fma_f32 v[108:109], v[108:109], v[220:221], v[164:165]
	v_pk_fma_f32 v[110:111], v[110:111], v[222:223], v[166:167]
	s_waitcnt vmcnt(18)
	v_pk_fma_f32 v[104:105], v[104:105], v[224:225], v[168:169]
	v_pk_fma_f32 v[106:107], v[106:107], v[226:227], v[170:171]
	s_waitcnt vmcnt(17)
	v_pk_fma_f32 v[100:101], v[100:101], v[228:229], v[172:173]
	v_pk_fma_f32 v[102:103], v[102:103], v[230:231], v[174:175]
	s_waitcnt vmcnt(16)
	v_pk_fma_f32 v[96:97], v[96:97], v[232:233], v[176:177]
	v_pk_fma_f32 v[98:99], v[98:99], v[234:235], v[178:179]
	global_store_dwordx4 v205, v[108:111], s[8:9]
	global_store_dwordx4 v205, v[104:107], s[8:9] offset:64
	global_store_dwordx4 v205, v[100:103], s[8:9] offset:512
	global_store_dwordx4 v205, v[96:99], s[8:9] offset:576
	global_load_dwordx4 v[164:167], v238, s[8:9]
	global_load_dwordx4 v[168:171], v238, s[8:9] offset:64
	global_load_dwordx4 v[172:175], v238, s[8:9] offset:512
	global_load_dwordx4 v[176:179], v238, s[8:9] offset:576
	s_waitcnt vmcnt(23)
	v_pk_fma_f32 v[92:93], v[92:93], v[220:221], v[180:181]
	v_pk_fma_f32 v[94:95], v[94:95], v[222:223], v[182:183]
	s_waitcnt vmcnt(22)
	v_pk_fma_f32 v[88:89], v[88:89], v[224:225], v[184:185]
	v_pk_fma_f32 v[90:91], v[90:91], v[226:227], v[186:187]
	s_waitcnt vmcnt(21)
	v_pk_fma_f32 v[84:85], v[84:85], v[228:229], v[188:189]
	v_pk_fma_f32 v[86:87], v[86:87], v[230:231], v[190:191]
	s_waitcnt vmcnt(20)
; #define PG8_BAR __builtin_amdgcn_s_barrier()
;     __device__ __forceinline__ void operator()(const f32x4 (&acc)[2][2][4][2], const Unit& u, int wr, int wc, int fr, int fq) const {
;     ...
;             for (int m = 0; m < 4; ++m) {
;                 const int row = u.pm * BM + ai * HALF + wr * 64 + m * 16 + fr;
;                 const float* s = row < MX_ ? src_main + (size_t)row * D_ : src_ctx + (size_t)(row - MX_) * D_;
;                 float* d = row < MX_ ? dst_main + (size_t)row * D_ : dst_ctx + (size_t)(row - MX_) * D_;
; #pragma unroll
;                 for (int bj = 0; bj < 2; ++bj)
; #pragma unroll
;                     for (int n = 0; n < 2; ++n) { const int off = col0 + bj * HALF + n * 16; const f32x4 xo = *(const f32x4*)(s + off); *(f32x4*)(d + off) = xo + gv[bj][n] * acc[ai][bj][m][n]; }
;     ...
;         if (!has_next) break;
; #pragma unroll
;         for (int a = 0; a < 2; ++a)
; #pragma unroll
;             for (int b = 0; b < 2; ++b)
; #pragma unroll
;                 for (int m = 0; m < 4; ++m)
; #pragma unroll
;                     for (int n = 0; n < 2; ++n) acc[a][b][m][n] = (f32x4){0.f, 0.f, 0.f, 0.f};
;         cur = nxt; cA = nA; cB = nB; ++ui;
;         if constexpr (ALIGN_EPI) { if (wr == 1) PG8_BAR; }
	v_pk_fma_f32 v[80:81], v[80:81], v[232:233], v[192:193]
	v_pk_fma_f32 v[82:83], v[82:83], v[234:235], v[194:195]
	global_store_dwordx4 v207, v[92:95], s[8:9]
	global_store_dwordx4 v207, v[88:91], s[8:9] offset:64
	global_store_dwordx4 v207, v[84:87], s[8:9] offset:512
	global_store_dwordx4 v207, v[80:83], s[8:9] offset:576
	global_load_dwordx4 v[180:183], v239, s[8:9]
	global_load_dwordx4 v[184:187], v239, s[8:9] offset:64
	global_load_dwordx4 v[188:191], v239, s[8:9] offset:512
	global_load_dwordx4 v[192:195], v239, s[8:9] offset:576
	s_waitcnt vmcnt(27)
	v_pk_fma_f32 v[76:77], v[76:77], v[220:221], v[196:197]
	v_pk_fma_f32 v[78:79], v[78:79], v[222:223], v[198:199]
	s_waitcnt vmcnt(26)
	v_pk_fma_f32 v[72:73], v[72:73], v[224:225], v[208:209]
	v_pk_fma_f32 v[74:75], v[74:75], v[226:227], v[210:211]
	s_waitcnt vmcnt(25)
	v_pk_fma_f32 v[68:69], v[68:69], v[228:229], v[212:213]
	v_pk_fma_f32 v[70:71], v[70:71], v[230:231], v[214:215]
	s_waitcnt vmcnt(24)
	v_pk_fma_f32 v[64:65], v[64:65], v[232:233], v[216:217]
	v_pk_fma_f32 v[66:67], v[66:67], v[234:235], v[218:219]
	global_store_dwordx4 v236, v[76:79], s[8:9]
	global_store_dwordx4 v236, v[72:75], s[8:9] offset:64
	global_store_dwordx4 v236, v[68:71], s[8:9] offset:512
	global_store_dwordx4 v236, v[64:67], s[8:9] offset:576
	global_load_dwordx4 v[196:199], v240, s[8:9]
	global_load_dwordx4 v[208:211], v240, s[8:9] offset:64
	global_load_dwordx4 v[212:215], v240, s[8:9] offset:512
	global_load_dwordx4 v[216:219], v240, s[8:9] offset:576
	s_waitcnt vmcnt(27)
	v_pk_fma_f32 v[60:61], v[60:61], v[220:221], v[128:129]
	v_pk_fma_f32 v[62:63], v[62:63], v[222:223], v[130:131]
	s_waitcnt vmcnt(26)
	v_pk_fma_f32 v[56:57], v[56:57], v[224:225], v[132:133]
	v_pk_fma_f32 v[58:59], v[58:59], v[226:227], v[134:135]
	s_waitcnt vmcnt(25)
	v_pk_fma_f32 v[52:53], v[52:53], v[228:229], v[136:137]
	v_pk_fma_f32 v[54:55], v[54:55], v[230:231], v[138:139]
	s_waitcnt vmcnt(24)
	v_pk_fma_f32 v[48:49], v[48:49], v[232:233], v[140:141]
	v_pk_fma_f32 v[50:51], v[50:51], v[234:235], v[142:143]
	global_store_dwordx4 v237, v[60:63], s[8:9]
	global_store_dwordx4 v237, v[56:59], s[8:9] offset:64
	global_store_dwordx4 v237, v[52:55], s[8:9] offset:512
	global_store_dwordx4 v237, v[48:51], s[8:9] offset:576
	s_waitcnt vmcnt(23)
	v_pk_fma_f32 v[44:45], v[44:45], v[220:221], v[164:165]
	v_pk_fma_f32 v[46:47], v[46:47], v[222:223], v[166:167]
	s_waitcnt vmcnt(22)
	v_pk_fma_f32 v[40:41], v[40:41], v[224:225], v[168:169]
	v_pk_fma_f32 v[42:43], v[42:43], v[226:227], v[170:171]
	s_waitcnt vmcnt(21)
	v_pk_fma_f32 v[36:37], v[36:37], v[228:229], v[172:173]
	v_pk_fma_f32 v[38:39], v[38:39], v[230:231], v[174:175]
	s_waitcnt vmcnt(20)
	v_pk_fma_f32 v[32:33], v[32:33], v[232:233], v[176:177]
	v_pk_fma_f32 v[34:35], v[34:35], v[234:235], v[178:179]
	global_store_dwordx4 v238, v[44:47], s[8:9]
	global_store_dwordx4 v238, v[40:43], s[8:9] offset:64
	global_store_dwordx4 v238, v[36:39], s[8:9] offset:512
	global_store_dwordx4 v238, v[32:35], s[8:9] offset:576
	s_waitcnt vmcnt(19)
	v_pk_fma_f32 v[28:29], v[28:29], v[220:221], v[180:181]
	v_pk_fma_f32 v[30:31], v[30:31], v[222:223], v[182:183]
	s_waitcnt vmcnt(18)
	v_pk_fma_f32 v[24:25], v[24:25], v[224:225], v[184:185]
	v_pk_fma_f32 v[26:27], v[26:27], v[226:227], v[186:187]
	s_waitcnt vmcnt(17)
	v_pk_fma_f32 v[20:21], v[20:21], v[228:229], v[188:189]
	v_pk_fma_f32 v[22:23], v[22:23], v[230:231], v[190:191]
	s_waitcnt vmcnt(16)
	v_pk_fma_f32 v[16:17], v[16:17], v[232:233], v[192:193]
	v_pk_fma_f32 v[18:19], v[18:19], v[234:235], v[194:195]
	global_store_dwordx4 v239, v[28:31], s[8:9]
	global_store_dwordx4 v239, v[24:27], s[8:9] offset:64
	global_store_dwordx4 v239, v[20:23], s[8:9] offset:512
	global_store_dwordx4 v239, v[16:19], s[8:9] offset:576
	s_waitcnt vmcnt(15)
	v_pk_fma_f32 v[12:13], v[12:13], v[220:221], v[196:197]
	v_pk_fma_f32 v[14:15], v[14:15], v[222:223], v[198:199]
	s_waitcnt vmcnt(14)
	v_pk_fma_f32 v[8:9], v[8:9], v[224:225], v[208:209]
	v_pk_fma_f32 v[10:11], v[10:11], v[226:227], v[210:211]
	s_waitcnt vmcnt(13)
	v_pk_fma_f32 v[4:5], v[4:5], v[228:229], v[212:213]
	v_pk_fma_f32 v[6:7], v[6:7], v[230:231], v[214:215]
	s_waitcnt vmcnt(12)
	v_pk_fma_f32 v[0:1], v[0:1], v[232:233], v[216:217]
	v_pk_fma_f32 v[2:3], v[2:3], v[234:235], v[218:219]
	global_store_dwordx4 v240, v[12:15], s[8:9]
	global_store_dwordx4 v240, v[8:11], s[8:9] offset:64
	global_store_dwordx4 v240, v[4:7], s[8:9] offset:512
	global_store_dwordx4 v240, v[0:3], s[8:9] offset:576
	s_andn2_b64 vcc, exec, s[6:7]
	s_mov_b64 s[6:7], -1
	s_cbranch_vccnz .LBB0_2326
	s_andn2_b64 vcc, exec, s[10:11]
	s_cbranch_vccnz .LBB0_2325
	s_barrier
	s_branch .LBB0_2325

;     __device__ __forceinline__ void operator()(const f32x4 (&acc)[2][2][4][2], const Unit& u, int wr, int wc, int fr, int fq) const {
;         const int cond = u.pm < 64 ? 0 : (u.pm < 128 ? 1 : 2);
;         const float* gate = gate_l + cond * 9216;
;         const int col0 = u.pn * BM + wc * 32 + 4 * fq;
;         f32x4 gv[2][2];
; #pragma unroll
;         for (int bj = 0; bj < 2; ++bj)
; #pragma unroll
;             for (int n = 0; n < 2; ++n) gv[bj][n] = *(const f32x4*)(gate + col0 + bj * HALF + n * 16) * coef;
; #pragma unroll
;         for (int ai = 0; ai < 2; ++ai)
; #pragma unroll
;             for (int m = 0; m < 4; ++m) {
;                 const int row = u.pm * BM + ai * HALF + wr * 64 + m * 16 + fr;
;                 const float* s = row < MX_ ? src_main + (size_t)row * D_ : src_ctx + (size_t)(row - MX_) * D_;
;                 float* d = row < MX_ ? dst_main + (size_t)row * D_ : dst_ctx + (size_t)(row - MX_) * D_;
; #pragma unroll
;                 for (int bj = 0; bj < 2; ++bj)
; #pragma unroll
;                     for (int n = 0; n < 2; ++n) { const int off = col0 + bj * HALF + n * 16; const f32x4 xo = *(const f32x4*)(s + off); *(f32x4*)(d + off) = xo + gv[bj][n] * acc[ai][bj][m][n]; }
.LBB0_2544:
	s_cmpk_lt_i32 s57, 0x80
	s_cselect_b32 s18, s54, 0x4800
	s_cmp_gt_i32 s57, 63
	s_cselect_b32 s18, s18, 0
	s_lshl_b32 s18, s18, 2
	s_add_u32 s18, s46, s18
	s_addc_u32 s19, s47, 0
	v_lshl_add_u32 v156, s57, 8, v158
	v_lshl_or_b32 v157, s58, 8, v160
	v_lshlrev_b32_e32 v200, 2, v157
	v_lshl_add_u32 v201, v156, 12, v200
	global_load_dwordx4 v[220:223], v200, s[18:19]
	global_load_dwordx4 v[224:227], v200, s[18:19] offset:64
	global_load_dwordx4 v[228:231], v200, s[18:19] offset:512
	global_load_dwordx4 v[232:235], v200, s[18:19] offset:576
	v_add_u32_e32 v205, 0x10000, v201
	v_add_u32_e32 v207, 0x20000, v201
	v_add_u32_e32 v252, 0x30000, v201
	v_add_u32_e32 v236, 0x80000, v201
	v_add_u32_e32 v237, 0x90000, v201
	v_add_u32_e32 v238, 0xa0000, v201
	v_add_u32_e32 v239, 0xb0000, v201
	global_load_dwordx4 v[140:143], v201, s[8:9]
	global_load_dwordx4 v[144:147], v201, s[8:9] offset:64
	global_load_dwordx4 v[148:151], v201, s[8:9] offset:512
	global_load_dwordx4 v[152:155], v201, s[8:9] offset:576
	global_load_dwordx4 v[164:167], v205, s[8:9]
	global_load_dwordx4 v[168:171], v205, s[8:9] offset:64
	global_load_dwordx4 v[172:175], v205, s[8:9] offset:512
	global_load_dwordx4 v[176:179], v205, s[8:9] offset:576
	global_load_dwordx4 v[180:183], v207, s[8:9]
	global_load_dwordx4 v[184:187], v207, s[8:9] offset:64
	global_load_dwordx4 v[188:191], v207, s[8:9] offset:512
	global_load_dwordx4 v[192:195], v207, s[8:9] offset:576
	global_load_dwordx4 v[196:199], v252, s[8:9]
	global_load_dwordx4 v[208:211], v252, s[8:9] offset:64
	global_load_dwordx4 v[212:215], v252, s[8:9] offset:512
	global_load_dwordx4 v[216:219], v252, s[8:9] offset:576
	s_waitcnt vmcnt(16)
	v_pk_mul_f32 v[220:221], v[220:221], 0.5 op_sel_hi:[1,0]
	v_pk_mul_f32 v[222:223], v[222:223], 0.5 op_sel_hi:[1,0]
	v_pk_mul_f32 v[224:225], v[224:225], 0.5 op_sel_hi:[1,0]
	v_pk_mul_f32 v[226:227], v[226:227], 0.5 op_sel_hi:[1,0]
	v_pk_mul_f32 v[228:229], v[228:229], 0.5 op_sel_hi:[1,0]
	v_pk_mul_f32 v[230:231], v[230:231], 0.5 op_sel_hi:[1,0]
	v_pk_mul_f32 v[232:233], v[232:233], 0.5 op_sel_hi:[1,0]
	v_pk_mul_f32 v[234:235], v[234:235], 0.5 op_sel_hi:[1,0]
	s_waitcnt vmcnt(15)
	v_pk_fma_f32 v[124:125], v[124:125], v[220:221], v[140:141]
	v_pk_fma_f32 v[126:127], v[126:127], v[222:223], v[142:143]
	s_waitcnt vmcnt(14)
	v_pk_fma_f32 v[120:121], v[120:121], v[224:225], v[144:145]
	v_pk_fma_f32 v[122:123], v[122:123], v[226:227], v[146:147]
	s_waitcnt vmcnt(13)
	v_pk_fma_f32 v[116:117], v[116:117], v[228:229], v[148:149]
	v_pk_fma_f32 v[118:119], v[118:119], v[230:231], v[150:151]
	s_waitcnt vmcnt(12)
	v_pk_fma_f32 v[112:113], v[112:113], v[232:233], v[152:153]
	v_pk_fma_f32 v[114:115], v[114:115], v[234:235], v[154:155]
	global_store_dwordx4 v201, v[124:127], s[8:9]
	global_store_dwordx4 v201, v[120:123], s[8:9] offset:64
	global_store_dwordx4 v201, v[116:119], s[8:9] offset:512
	global_store_dwordx4 v201, v[112:115], s[8:9] offset:576
	global_load_dwordx4 v[140:143], v236, s[8:9]
	global_load_dwordx4 v[144:147], v236, s[8:9] offset:64
	global_load_dwordx4 v[148:151], v236, s[8:9] offset:512
	global_load_dwordx4 v[152:155], v236, s[8:9] offset:576
	s_waitcnt vmcnt(19)
	v_pk_fma_f32 v[108:109], v[108:109], v[220:221], v[164:165]
	v_pk_fma_f32 v[110:111], v[110:111], v[222:223], v[166:167]
	s_waitcnt vmcnt(18)
	v_pk_fma_f32 v[104:105], v[104:105], v[224:225], v[168:169]
	v_pk_fma_f32 v[106:107], v[106:107], v[226:227], v[170:171]
	s_waitcnt vmcnt(17)
	v_pk_fma_f32 v[100:101], v[100:101], v[228:229], v[172:173]
	v_pk_fma_f32 v[102:103], v[102:103], v[230:231], v[174:175]
	s_waitcnt vmcnt(16)
	v_pk_fma_f32 v[96:97], v[96:97], v[232:233], v[176:177]
	v_pk_fma_f32 v[98:99], v[98:99], v[234:235], v[178:179]
	global_store_dwordx4 v205, v[108:111], s[8:9]
	global_store_dwordx4 v205, v[104:107], s[8:9] offset:64
	global_store_dwordx4 v205, v[100:103], s[8:9] offset:512
	global_store_dwordx4 v205, v[96:99], s[8:9] offset:576
	global_load_dwordx4 v[164:167], v237, s[8:9]
	global_load_dwordx4 v[168:171], v237, s[8:9] offset:64
	global_load_dwordx4 v[172:175], v237, s[8:9] offset:512
	global_load_dwordx4 v[176:179], v237, s[8:9] offset:576
	s_waitcnt vmcnt(23)
	v_pk_fma_f32 v[92:93], v[92:93], v[220:221], v[180:181]
	v_pk_fma_f32 v[94:95], v[94:95], v[222:223], v[182:183]
	s_waitcnt vmcnt(22)
	v_pk_fma_f32 v[88:89], v[88:89], v[224:225], v[184:185]
	v_pk_fma_f32 v[90:91], v[90:91], v[226:227], v[186:187]
	s_waitcnt vmcnt(21)
	v_pk_fma_f32 v[84:85], v[84:85], v[228:229], v[188:189]
	v_pk_fma_f32 v[86:87], v[86:87], v[230:231], v[190:191]
	s_waitcnt vmcnt(20)
; #define PG8_BAR __builtin_amdgcn_s_barrier()
;     __device__ __forceinline__ void operator()(const f32x4 (&acc)[2][2][4][2], const Unit& u, int wr, int wc, int fr, int fq) const {
;     ...
;             for (int m = 0; m < 4; ++m) {
;                 const int row = u.pm * BM + ai * HALF + wr * 64 + m * 16 + fr;
;                 const float* s = row < MX_ ? src_main + (size_t)row * D_ : src_ctx + (size_t)(row - MX_) * D_;
;                 float* d = row < MX_ ? dst_main + (size_t)row * D_ : dst_ctx + (size_t)(row - MX_) * D_;
; #pragma unroll
;                 for (int bj = 0; bj < 2; ++bj)
; #pragma unroll
;                     for (int n = 0; n < 2; ++n) { const int off = col0 + bj * HALF + n * 16; const f32x4 xo = *(const f32x4*)(s + off); *(f32x4*)(d + off) = xo + gv[bj][n] * acc[ai][bj][m][n]; }
;     ...
;         if (!has_next) break;
; #pragma unroll
;         for (int a = 0; a < 2; ++a)
; #pragma unroll
;             for (int b = 0; b < 2; ++b)
; #pragma unroll
;                 for (int m = 0; m < 4; ++m)
; #pragma unroll
;                     for (int n = 0; n < 2; ++n) acc[a][b][m][n] = (f32x4){0.f, 0.f, 0.f, 0.f};
;         cur = nxt; cA = nA; cB = nB; ++ui;
;         if constexpr (ALIGN_EPI) { if (wr == 1) PG8_BAR; }
	v_pk_fma_f32 v[80:81], v[80:81], v[232:233], v[192:193]
	v_pk_fma_f32 v[82:83], v[82:83], v[234:235], v[194:195]
	global_store_dwordx4 v207, v[92:95], s[8:9]
	global_store_dwordx4 v207, v[88:91], s[8:9] offset:64
	global_store_dwordx4 v207, v[84:87], s[8:9] offset:512
	global_store_dwordx4 v207, v[80:83], s[8:9] offset:576
	global_load_dwordx4 v[180:183], v238, s[8:9]
	global_load_dwordx4 v[184:187], v238, s[8:9] offset:64
	global_load_dwordx4 v[188:191], v238, s[8:9] offset:512
	global_load_dwordx4 v[192:195], v238, s[8:9] offset:576
	s_waitcnt vmcnt(27)
	v_pk_fma_f32 v[76:77], v[76:77], v[220:221], v[196:197]
	v_pk_fma_f32 v[78:79], v[78:79], v[222:223], v[198:199]
	s_waitcnt vmcnt(26)
	v_pk_fma_f32 v[72:73], v[72:73], v[224:225], v[208:209]
	v_pk_fma_f32 v[74:75], v[74:75], v[226:227], v[210:211]
	s_waitcnt vmcnt(25)
	v_pk_fma_f32 v[68:69], v[68:69], v[228:229], v[212:213]
	v_pk_fma_f32 v[70:71], v[70:71], v[230:231], v[214:215]
	s_waitcnt vmcnt(24)
	v_pk_fma_f32 v[64:65], v[64:65], v[232:233], v[216:217]
	v_pk_fma_f32 v[66:67], v[66:67], v[234:235], v[218:219]
	global_store_dwordx4 v252, v[76:79], s[8:9]
	global_store_dwordx4 v252, v[72:75], s[8:9] offset:64
	global_store_dwordx4 v252, v[68:71], s[8:9] offset:512
	global_store_dwordx4 v252, v[64:67], s[8:9] offset:576
	global_load_dwordx4 v[196:199], v239, s[8:9]
	global_load_dwordx4 v[208:211], v239, s[8:9] offset:64
	global_load_dwordx4 v[212:215], v239, s[8:9] offset:512
	global_load_dwordx4 v[216:219], v239, s[8:9] offset:576
	s_waitcnt vmcnt(27)
	v_pk_fma_f32 v[60:61], v[60:61], v[220:221], v[140:141]
	v_pk_fma_f32 v[62:63], v[62:63], v[222:223], v[142:143]
	s_waitcnt vmcnt(26)
	v_pk_fma_f32 v[56:57], v[56:57], v[224:225], v[144:145]
	v_pk_fma_f32 v[58:59], v[58:59], v[226:227], v[146:147]
	s_waitcnt vmcnt(25)
	v_pk_fma_f32 v[52:53], v[52:53], v[228:229], v[148:149]
	v_pk_fma_f32 v[54:55], v[54:55], v[230:231], v[150:151]
	s_waitcnt vmcnt(24)
	v_pk_fma_f32 v[48:49], v[48:49], v[232:233], v[152:153]
	v_pk_fma_f32 v[50:51], v[50:51], v[234:235], v[154:155]
	global_store_dwordx4 v236, v[60:63], s[8:9]
	global_store_dwordx4 v236, v[56:59], s[8:9] offset:64
	global_store_dwordx4 v236, v[52:55], s[8:9] offset:512
	global_store_dwordx4 v236, v[48:51], s[8:9] offset:576
	s_waitcnt vmcnt(23)
	v_pk_fma_f32 v[44:45], v[44:45], v[220:221], v[164:165]
	v_pk_fma_f32 v[46:47], v[46:47], v[222:223], v[166:167]
	s_waitcnt vmcnt(22)
	v_pk_fma_f32 v[40:41], v[40:41], v[224:225], v[168:169]
	v_pk_fma_f32 v[42:43], v[42:43], v[226:227], v[170:171]
	s_waitcnt vmcnt(21)
	v_pk_fma_f32 v[36:37], v[36:37], v[228:229], v[172:173]
	v_pk_fma_f32 v[38:39], v[38:39], v[230:231], v[174:175]
	s_waitcnt vmcnt(20)
	v_pk_fma_f32 v[32:33], v[32:33], v[232:233], v[176:177]
	v_pk_fma_f32 v[34:35], v[34:35], v[234:235], v[178:179]
	global_store_dwordx4 v237, v[44:47], s[8:9]
	global_store_dwordx4 v237, v[40:43], s[8:9] offset:64
	global_store_dwordx4 v237, v[36:39], s[8:9] offset:512
	global_store_dwordx4 v237, v[32:35], s[8:9] offset:576
	s_waitcnt vmcnt(19)
	v_pk_fma_f32 v[28:29], v[28:29], v[220:221], v[180:181]
	v_pk_fma_f32 v[30:31], v[30:31], v[222:223], v[182:183]
	s_waitcnt vmcnt(18)
	v_pk_fma_f32 v[24:25], v[24:25], v[224:225], v[184:185]
	v_pk_fma_f32 v[26:27], v[26:27], v[226:227], v[186:187]
	s_waitcnt vmcnt(17)
	v_pk_fma_f32 v[20:21], v[20:21], v[228:229], v[188:189]
	v_pk_fma_f32 v[22:23], v[22:23], v[230:231], v[190:191]
	s_waitcnt vmcnt(16)
	v_pk_fma_f32 v[16:17], v[16:17], v[232:233], v[192:193]
	v_pk_fma_f32 v[18:19], v[18:19], v[234:235], v[194:195]
	global_store_dwordx4 v238, v[28:31], s[8:9]
	global_store_dwordx4 v238, v[24:27], s[8:9] offset:64
	global_store_dwordx4 v238, v[20:23], s[8:9] offset:512
	global_store_dwordx4 v238, v[16:19], s[8:9] offset:576
	s_waitcnt vmcnt(15)
	v_pk_fma_f32 v[12:13], v[12:13], v[220:221], v[196:197]
	v_pk_fma_f32 v[14:15], v[14:15], v[222:223], v[198:199]
	s_waitcnt vmcnt(14)
	v_pk_fma_f32 v[8:9], v[8:9], v[224:225], v[208:209]
	v_pk_fma_f32 v[10:11], v[10:11], v[226:227], v[210:211]
	s_waitcnt vmcnt(13)
	v_pk_fma_f32 v[4:5], v[4:5], v[228:229], v[212:213]
	v_pk_fma_f32 v[6:7], v[6:7], v[230:231], v[214:215]
	s_waitcnt vmcnt(12)
	v_pk_fma_f32 v[0:1], v[0:1], v[232:233], v[216:217]
	v_pk_fma_f32 v[2:3], v[2:3], v[234:235], v[218:219]
	global_store_dwordx4 v239, v[12:15], s[8:9]
	global_store_dwordx4 v239, v[8:11], s[8:9] offset:64
	global_store_dwordx4 v239, v[4:7], s[8:9] offset:512
	global_store_dwordx4 v239, v[0:3], s[8:9] offset:576
	s_and_b64 vcc, exec, s[4:5]
	s_mov_b64 s[4:5], -1
	s_cbranch_vccnz .LBB0_2529
	s_andn2_b64 vcc, exec, s[10:11]
	s_cbranch_vccnz .LBB0_2528
	s_barrier
	s_branch .LBB0_2528
